# chain: state-update MFMA pairs merged into single K=32 MFMAs ([bt|kt] x [up;vt])
# baseline (speedup 1.0000x reference)
; #define LAS __attribute__((address_space(3)))
; __device__ void phase_rwkv_dist(const Params& p, LAS unsigned char* lds, int wg, int nwg) {
;     ...
;             for (int ci = 0; ci < RC_NCHK; ++ci) {
;                 { unsigned sp = 0; while (!dead && lflag[ci % RD_NL] != (unsigned)(ci + 1)) { __builtin_amdgcn_s_sleep(1); if (++sp > RD_SPIN_MAX) { if (lane == 0) atomicAdd(ERR, 1u); dead = true; } } }
;                 asm volatile("" ::: "memory");
;                 LAS const unsigned char* sl = lds + (ci % RD_NL) * RC_SL;
;                 const bf16x8 at0 = *(LAS const bf16x8*)(sl + RC_AT + lane * 16), at1 = *(LAS const bf16x8*)(sl + RC_AT + 1024 + lane * 16);
;                 const bf16x8 rt0 = *(LAS const bf16x8*)(sl + RC_RT + lane * 16), rt1 = *(LAS const bf16x8*)(sl + RC_RT + 1024 + lane * 16);
;                 const bf16x8 mm0 = *(LAS const bf16x8*)(sl + RD_MM + lane * 32), mm1 = *(LAS const bf16x8*)(sl + RD_MM + lane * 32 + 16);
;                 const bf16x4 vt = *(LAS const bf16x4*)(sl + RC_VT + lane * 8);
;                 bf16x8 bk[4]; f32x4 gl[4];
; #pragma unroll
;                 for (int ct = 0; ct < 4; ++ct) { bk[ct] = *(LAS const bf16x8*)(sl + RD_BK + (ct * 64 + lane) * 16); gl[ct] = *(LAS const f32x4*)(sl + RC_GL + (16 * ct + 4 * q) * 4); }
;                 asm volatile("s_waitcnt lgkmcnt(0)" ::: "memory");
;                 lflag[12] = (unsigned)(ci + 1);
;                 const bf16x4 mak = __builtin_shufflevector(mm0, mm0, 0, 1, 2, 3), mrb = __builtin_shufflevector(mm0, mm0, 4, 5, 6, 7), mrk = __builtin_shufflevector(mm1, mm1, 0, 1, 2, 3), ti = __builtin_shufflevector(mm1, mm1, 4, 5, 6, 7);
;                 const bf16x8 sop0 = pk8(Sacc[0], Sacc[1]), sop1 = pk8(Sacc[2], Sacc[3]);
;                 f32x4 X = MFMA32(at0, sop0, zero4); X = MFMA32(at1, sop1, X); X = MFMA16(mak, vt, X);
;                 const f32x4 U = MFMA16(ti, pk4(X), zero4);
;                 const bf16x4 up = pk4(U);
;                 f32x4 Y = MFMA32(rt0, sop0, zero4); Y = MFMA32(rt1, sop1, Y); Y = MFMA16(mrb, up, Y); Y = MFMA16(mrk, vt, Y);
; #pragma unroll
;                 for (int ct = 0; ct < 4; ++ct) { const bf16x4 btc = __builtin_shufflevector(bk[ct], bk[ct], 0, 1, 2, 3), ktc = __builtin_shufflevector(bk[ct], bk[ct], 4, 5, 6, 7);
;                     Sacc[ct] = MFMA16(btc, up, Sacc[ct]); Sacc[ct] = MFMA16(ktc, vt, Sacc[ct]); Sacc[ct] = Sacc[ct] * gl[ct]; }
.LBB0_778:
	s_waitcnt lgkmcnt(0)
	s_mulk_i32 s16, 0x2b00
	s_add_i32 s2, s16, 0
	s_mul_hi_u32 s98, s7, 0xaaaaaaab
	s_lshr_b32 s98, s98, 3
	s_mul_i32 s98, s98, 12
	s_sub_i32 s98, s7, s98
	s_lshl_b32 s98, s98, 2
	s_add_i32 s98, s98, 0x27400
	v_add_u32_e32 v0, s2, v196
	v_add_u32_e32 v90, s2, v198
	v_add_u32_e32 v82, s2, v203
	v_add_u32_e32 v98, s2, v189
	ds_read_b128 v[104:107], v0
	ds_read_b128 v[108:111], v0 offset:1024
	ds_read_b128 v[112:115], v90 offset:8192
	ds_read_b64 v[102:103], v82 offset:10240
	ds_read_b128 v[120:123], v90 offset:8208
	ds_read_b128 v[116:119], v0 offset:2048
	ds_read_b128 v[128:131], v0 offset:3072
	ds_read_b128 v[132:135], v0 offset:4096
	ds_read_b128 v[136:139], v0 offset:5120
	ds_read_b128 v[140:143], v0 offset:6144
	ds_read_b128 v[144:147], v0 offset:7168
	ds_read_b128 v[124:127], v98 offset:10752
	ds_read_b128 v[160:163], v98 offset:10816
	ds_read_b128 v[168:171], v98 offset:10880
	ds_read_b128 v[176:179], v98 offset:10944
	v_cvt_pk_bf16_f32 v82, v56, v57
	v_cvt_pk_bf16_f32 v83, v58, v59
	v_cvt_pk_bf16_f32 v84, v64, v65
	v_cvt_pk_bf16_f32 v85, v66, v67
	v_cvt_pk_bf16_f32 v86, v60, v61
	v_cvt_pk_bf16_f32 v87, v62, v63
	v_cvt_pk_bf16_f32 v88, v52, v53
	v_cvt_pk_bf16_f32 v89, v54, v55
	s_lshl_b32 s72, s6, 4
	s_cmpk_eq_i32 s7, 0x200
	s_mov_b32 s6, s7
	s_waitcnt lgkmcnt(14)
	v_mfma_f32_16x16x32_bf16 v[70:73], v[104:107], v[82:85], 0
	s_waitcnt lgkmcnt(13)
	v_mfma_f32_16x16x32_bf16 v[70:73], v[108:111], v[86:89], v[70:73]
	s_waitcnt lgkmcnt(9)
	v_mfma_f32_16x16x32_bf16 v[180:183], v[116:119], v[82:85], 0
	s_waitcnt lgkmcnt(8)
	v_mfma_f32_16x16x32_bf16 v[180:183], v[128:131], v[86:89], v[180:183]
	s_nop 4
	v_mfma_f32_16x16x16_bf16 v[70:73], v[112:113], v[102:103], v[70:73]
	s_nop 7
	v_cvt_pk_bf16_f32 v70, v70, v71
	v_cvt_pk_bf16_f32 v71, v72, v73
	s_nop 1
	v_mfma_f32_16x16x16_bf16 v[70:73], v[122:123], v[70:71], 0
	s_nop 3
	v_mfma_f32_16x16x16_bf16 v[180:183], v[120:121], v[102:103], v[180:183]
	s_nop 2
	v_cvt_pk_bf16_f32 v100, v70, v71
	v_cvt_pk_bf16_f32 v101, v72, v73
	s_waitcnt lgkmcnt(4)
	s_nop 0
	v_mfma_f32_16x16x32_bf16 v[56:59], v[132:135], v[100:103], v[56:59]
	v_mfma_f32_16x16x32_bf16 v[64:67], v[136:139], v[100:103], v[64:67]
	v_mfma_f32_16x16x32_bf16 v[60:63], v[140:143], v[100:103], v[60:63]
	v_mfma_f32_16x16x32_bf16 v[52:55], v[144:147], v[100:103], v[52:55]
	v_mfma_f32_16x16x16_bf16 v[180:183], v[114:115], v[100:101], v[180:183]
	s_nop 3
	s_waitcnt lgkmcnt(0)
	v_mov_b32_e32 v0, s50
	v_mov_b32_e32 v184, s7
	ds_write_b32 v0, v184
	v_mov_b32_e32 v185, s98
	ds_read_b32 v185, v185
	v_pk_mul_f32 v[56:57], v[124:125], v[56:57]
	v_pk_mul_f32 v[58:59], v[126:127], v[58:59]
	v_pk_mul_f32 v[64:65], v[160:161], v[64:65]
	v_pk_mul_f32 v[66:67], v[162:163], v[66:67]
	v_pk_mul_f32 v[60:61], v[168:169], v[60:61]
	v_pk_mul_f32 v[62:63], v[170:171], v[62:63]
	v_pk_mul_f32 v[52:53], v[176:177], v[52:53]
	v_pk_mul_f32 v[54:55], v[178:179], v[54:55]
	v_cvt_pk_bf16_f32 v70, v180, v181
	v_cvt_pk_bf16_f32 v71, v182, v183
	v_lshl_add_u64 v[166:167], v[2:3], 0, s[72:73]
	v_lshlrev_b64 v[166:167], 7, v[166:167]
	v_mfma_f32_16x16x16_bf16 v[70:73], v[70:71], v[150:151], 0
	v_lshl_add_u64 v[166:167], v[68:69], 0, v[166:167]
	s_nop 7
	v_cvt_pk_bf16_f32 v70, v70, v71
	v_cvt_pk_bf16_f32 v71, v72, v73
	global_store_dwordx2 v[166:167], v[70:71], off
	s_cbranch_scc1 .LBB0_789
